# adds: attention epilogue reads g_subln from LDS (no store->load serialization); static s_setprio 1 for waves 4-7 in the fast attention loop
# speedup vs baseline: 1.0339x; 1.0092x over previous
; DI void attn_item(const Params& p, char* lds, int S, const bfr* Qb, const bfr* Kb, const bfr* Vtb, int h, int q0, int tok0) {
;   const int tid = threadIdx.x, w = __builtin_amdgcn_readfirstlane(tid >> 6), lane = tid & 63, r = lane & 31, h8 = lane >> 5;
;   const int c = w & 1, qg = w >> 1;
;   f32x16 O[2][4];
; #pragma unroll
;   for (int t = 0; t < 2; ++t)
; #pragma unroll
;     for (int e = 0; e < 4; ++e)
; #pragma unroll
;       for (int i = 0; i < 16; ++i) O[t][e][i] = 0.f;
;   float m[2] = {-64.f, -64.f}, l[2] = {0.f, 0.f};
;   const int nkt = S >> 5;
;   int voffK[4];
; #pragma unroll
;   for (int ks = 0; ks < 4; ++ks) voffK[ks] = r * 128 + (((ks * 2 + h8) ^ ((r >> 1) & 7)) << 4);
;   const int voffV0 = r * 64 + ((h8 ^ ((r >> 2) & 3)) << 4);
;   const int lr = lane >> 3, sl = lane & 7;
;   const char* k0p = (const char*)(Kb + (size_t)(h * 2) * S * 64);
;   const char* k1p = (const char*)(Kb + (size_t)(h * 2 + 1) * S * 64);
;   const char* vtp = (const char*)Vtb;
;   unsigned ko, vo;
;   { const int row = (w & 3) * 8 + lr; ko = (unsigned)(row * 128 + ((sl ^ ((row >> 1) & 7)) << 4)); }
;   { const int row = w * 16 + (lane >> 2); vo = (unsigned)(row * 64 + (((lane & 3) ^ ((row >> 2) & 3)) << 4)); }
.LBB0_152:
.LBB0_153:
	v_bfe_u32 v2, v0, 5, 1
	v_and_b32_e32 v3, 31, v0
	v_lshrrev_b32_e32 v5, 1, v0
	v_lshlrev_b32_e32 v4, 7, v3
	v_bfe_u32 v6, v0, 1, 3
	v_bitop3_b32 v5, v2, v5, 7 bitop3:0x78
	v_lshl_or_b32 v203, v5, 4, v4
	v_bitop3_b32 v5, v2, v6, 2 bitop3:0x36
	v_lshl_or_b32 v204, v5, 4, v4
	v_bitop3_b32 v5, v2, v6, 4 bitop3:0x36
	v_lshl_or_b32 v205, v5, 4, v4
	v_bitop3_b32 v5, v2, v6, 6 bitop3:0x36
	v_lshl_or_b32 v206, v5, 4, v4
	v_lshrrev_b32_e32 v4, 2, v0
	s_load_dwordx2 s[18:19], s[74:75], 0xe0
	v_bitop3_b32 v2, v2, v4, 3 bitop3:0x78
	v_lshlrev_b32_e32 v2, 4, v2
	v_lshlrev_b32_e32 v3, 6, v3
	s_waitcnt lgkmcnt(0)
	s_load_dwordx8 s[8:15], s[74:75], 0x50
	s_load_dwordx2 s[20:21], s[74:75], 0x70
	v_and_b32_e32 v1, 0x3ff, v0
	v_or_b32_e32 v209, v2, v3
	v_bitop3_b32 v210, v2, 32, v3 bitop3:0x36
	v_mbcnt_lo_u32_b32 v2, -1, 0
	s_movk_i32 s0, 0x3ff
	v_lshlrev_b32_e32 v4, 4, v1
	v_mbcnt_hi_u32_b32 v212, -1, v2
	v_bfe_u32 v207, v0, 3, 3
	v_and_b32_e32 v5, 0x3c0, v4
	v_bitop3_b32 v4, v4, v0, s0 bitop3:0x78
	s_add_u32 s22, s18, 0x6894400
	v_and_b32_e32 v2, 64, v212
	v_and_b32_e32 v202, 63, v0
	v_and_or_b32 v208, v4, 48, v5
	s_addc_u32 s23, s19, 0
	v_lshlrev_b32_e32 v211, 7, v207
	s_mov_b32 s25, 0
	v_mov_b32_e32 v3, 0
	s_mov_b64 s[26:27], 0x800
	s_mov_b64 s[28:29], 0x18894400
	s_mov_b64 s[30:31], 0x1e894400
	s_mov_b64 s[34:35], 0x18895400
	s_mov_b64 s[36:37], 0x1e896400
	s_mov_b64 s[42:43], 0x18896400
	s_mov_b64 s[44:45], 0x1e898400
	s_mov_b64 s[46:47], 0x18897400
	s_mov_b64 s[48:49], 0x1e89a400
	v_xor_b32_e32 v213, 32, v212
	v_add_u32_e32 v214, 64, v2
	s_mov_b32 s33, 0x40c00000
	s_mov_b64 s[50:51], 0x1000
	s_mov_b64 s[52:53], 0x2000
	v_mov_b32_e32 v215, 0x358637bd
	s_mov_b32 s40, 0x800000
	s_mov_b32 s41, s2
	s_mov_b32 s54, s2
	s_waitcnt lgkmcnt(0)
	v_lshlrev_b32_e32 v2, 2, v1
	v_cmp_gt_u32_e32 vcc, 0x200, v2
	s_nop 1
	s_and_saveexec_b64 s[0:1], vcc
	global_load_dword v4, v2, s[20:21]
	v_add_u32_e32 v5, 0x20000, v2
	s_waitcnt vmcnt(0)
	ds_write_b32 v5, v4
	s_waitcnt lgkmcnt(0)
	s_or_b64 exec, exec, s[0:1]
	s_load_dwordx2 s[0:1], s[74:75], 0x40
	s_load_dwordx2 s[4:5], s[74:75], 0x48
	v_lshlrev_b32_e32 v2, 2, v202
	s_waitcnt lgkmcnt(0)
	global_load_dword v4, v2, s[0:1]
	global_load_dword v5, v2, s[4:5]
	s_mov_b32 s98, 0
	s_mov_b32 s99, 0
	s_mov_b32 s100, 0
	s_waitcnt vmcnt(0)
	v_and_b32_e32 v4, 0x7fffffff, v4
	v_and_b32_e32 v5, 0x7fffffff, v5
	s_nop 1
.Lfa_gmax:
	v_readlane_b32 s0, v4, s100
	v_readlane_b32 s1, v5, s100
	s_nop 3
	s_max_u32 s98, s98, s0
	s_max_u32 s99, s99, s1
	s_add_u32 s100, s100, 1
	s_cmp_lt_u32 s100, 64
	s_cbranch_scc1 .Lfa_gmax
	v_mov_b32_e32 v2, s98
	v_mul_f32_e32 v2, s99, v2
	s_nop 0
	v_cmp_gt_f32_e32 vcc, 0x40400000, v2
	s_nop 3
	s_cmp_lg_u64 vcc, 0
	s_cselect_b32 s99, 1, 0
	s_nop 0
	s_branch .LBB0_155

; DI unsigned pk2(float a, float b) { fl2_t f = {a, b}; bf2_t r = __builtin_convertvector(f, bf2_t); return __builtin_bit_cast(unsigned, r); }
; DI void attn_item(const Params& p, char* lds, int S, const bfr* Qb, const bfr* Kb, const bfr* Vtb, int h, int q0, int tok0) {
;     ...
;   if (c_e == 0) {
; #pragma unroll
;     for (int t = 0; t < 2; ++t) {
;       float ss = 0.f;
; #pragma unroll
;       for (int e = 0; e < 4; ++e)
; #pragma unroll
;         for (int i = 0; i < 16; ++i) { float o = O[t][e][i] - xch[((qg_e * 2 + t) * 64 + e * 16 + i) * 64 + lane_e]; O[t][e][i] = o; ss += o * o; }
;       ss += __shfl_xor(ss, 32, 64);
;       const float rstd = rsqrtf(ss * (1.f / 128.f) + 1e-6f) * 0.8f;
;       bfr* dst = (bfr*)(p.ws + WS_H) + (size_t)(tok0 + q0 + qg_e * 64 + t * 32 + r_e) * D + h * 128;
; #pragma unroll
;       for (int e = 0; e < 4; ++e)
; #pragma unroll
;         for (int g = 0; g < 4; ++g) {
;           const int e0 = e * 32 + 8 * g + 4 * h8_e;
;           float4 gs = *(const float4*)(p.g_subln + e0);
;           u32x2 o;
;           o[0] = pk2(O[t][e][4 * g + 0] * rstd * gs.x, O[t][e][4 * g + 1] * rstd * gs.y);
.LBB0_185:
	s_and_b64 vcc, exec, s[0:1]
	s_waitcnt lgkmcnt(0)
	s_barrier
	s_cbranch_vccz .LBB0_154
	s_ashr_i32 s0, s3, 1
	s_add_i32 s56, s56, s55
	s_andn2_b32 s0, s0, 63
	v_and_b32_e32 v2, 31, v148
	s_add_i32 s0, s0, s56
	v_add_u32_e32 v132, s0, v2
	v_lshrrev_b32_e32 v2, 3, v148
	ds_read2st64_b32 v[136:137], v217 offset1:1
	ds_read2st64_b32 v[144:145], v217 offset0:2 offset1:3
	ds_read2st64_b32 v[138:139], v217 offset0:4 offset1:5
	ds_read2st64_b32 v[146:147], v217 offset0:6 offset1:7
	ds_read2st64_b32 v[140:141], v217 offset0:8 offset1:9
	ds_read2st64_b32 v[150:151], v217 offset0:10 offset1:11
	ds_read2st64_b32 v[142:143], v217 offset0:12 offset1:13
	ds_read2st64_b32 v[154:155], v217 offset0:14 offset1:15
	ds_read2st64_b32 v[148:149], v217 offset0:16 offset1:17
	ds_read2st64_b32 v[158:159], v217 offset0:18 offset1:19
	ds_read2st64_b32 v[152:153], v217 offset0:20 offset1:21
	ds_read2st64_b32 v[162:163], v217 offset0:22 offset1:23
	ds_read2st64_b32 v[156:157], v217 offset0:24 offset1:25
	ds_read2st64_b32 v[166:167], v217 offset0:26 offset1:27
	ds_read2st64_b32 v[160:161], v217 offset0:28 offset1:29
	ds_read2st64_b32 v[170:171], v217 offset0:30 offset1:31
	ds_read2st64_b32 v[164:165], v217 offset0:32 offset1:33
	ds_read2st64_b32 v[174:175], v217 offset0:34 offset1:35
	ds_read2st64_b32 v[168:169], v217 offset0:36 offset1:37
	ds_read2st64_b32 v[178:179], v217 offset0:38 offset1:39
	ds_read2st64_b32 v[172:173], v217 offset0:40 offset1:41
	ds_read2st64_b32 v[182:183], v217 offset0:42 offset1:43
	ds_read2st64_b32 v[176:177], v217 offset0:44 offset1:45
	ds_read2st64_b32 v[186:187], v217 offset0:46 offset1:47
	ds_read2st64_b32 v[180:181], v217 offset0:48 offset1:49
	ds_read2st64_b32 v[188:189], v217 offset0:50 offset1:51
	ds_read2st64_b32 v[184:185], v217 offset0:52 offset1:53
	ds_read2st64_b32 v[190:191], v217 offset0:54 offset1:55
	ds_read2st64_b32 v[196:197], v217 offset0:60 offset1:61
	ds_read2st64_b32 v[134:135], v217 offset0:62 offset1:64
	v_or_b32_e32 v133, 0x3f00, v218
	v_and_b32_e32 v2, 4, v2
	ds_read_b32 v199, v133
	ds_read2st64_b32 v[192:193], v217 offset0:56 offset1:57
	ds_read2st64_b32 v[194:195], v217 offset0:58 offset1:59
	ds_read2st64_b32 v[200:201], v217 offset0:65 offset1:66
	s_waitcnt lgkmcnt(14)
	v_pk_add_f32 v[116:117], v[116:117], v[136:137] neg_lo:[0,1] neg_hi:[0,1]
	s_waitcnt lgkmcnt(4)
	v_mov_b32_e32 v198, v134
	v_lshlrev_b32_e32 v134, 2, v2
	v_add_u32_e32 v255, 0x20000, v134
	v_pk_add_f32 v[118:119], v[118:119], v[144:145] neg_lo:[0,1] neg_hi:[0,1]
	v_pk_mul_f32 v[136:137], v[116:117], v[116:117]
	v_pk_add_f32 v[80:81], v[80:81], v[196:197] neg_lo:[0,1] neg_hi:[0,1]
	s_waitcnt lgkmcnt(3)
	v_pk_add_f32 v[82:83], v[82:83], v[198:199] neg_lo:[0,1] neg_hi:[0,1]
	v_pk_mul_f32 v[144:145], v[118:119], v[118:119]
	ds_read_b128 v[196:199], v255
	v_add_f32_e32 v133, v136, v137
	v_pk_add_f32 v[120:121], v[120:121], v[138:139] neg_lo:[0,1] neg_hi:[0,1]
	v_add_f32_e32 v133, v133, v144
	v_pk_mul_f32 v[138:139], v[120:121], v[120:121]
	v_add_f32_e32 v133, v133, v145
	v_pk_add_f32 v[122:123], v[122:123], v[146:147] neg_lo:[0,1] neg_hi:[0,1]
	v_add_f32_e32 v133, v133, v138
	v_pk_mul_f32 v[146:147], v[122:123], v[122:123]
	v_add_f32_e32 v133, v133, v139
	v_pk_add_f32 v[124:125], v[124:125], v[140:141] neg_lo:[0,1] neg_hi:[0,1]
	v_add_f32_e32 v133, v133, v146
	v_pk_mul_f32 v[140:141], v[124:125], v[124:125]
	v_add_f32_e32 v133, v133, v147
	v_pk_add_f32 v[126:127], v[126:127], v[150:151] neg_lo:[0,1] neg_hi:[0,1]
	v_add_f32_e32 v133, v133, v140
	v_pk_mul_f32 v[150:151], v[126:127], v[126:127]
	v_add_f32_e32 v133, v133, v141
	v_pk_add_f32 v[128:129], v[128:129], v[142:143] neg_lo:[0,1] neg_hi:[0,1]
	v_add_f32_e32 v133, v133, v150
	v_pk_mul_f32 v[142:143], v[128:129], v[128:129]
	v_add_f32_e32 v133, v133, v151
	v_pk_add_f32 v[130:131], v[130:131], v[154:155] neg_lo:[0,1] neg_hi:[0,1]
	v_add_f32_e32 v133, v133, v142
	v_pk_mul_f32 v[154:155], v[130:131], v[130:131]
	v_add_f32_e32 v133, v133, v143
	v_pk_add_f32 v[100:101], v[100:101], v[148:149] neg_lo:[0,1] neg_hi:[0,1]
	v_add_f32_e32 v133, v133, v154
	v_pk_mul_f32 v[148:149], v[100:101], v[100:101]
	v_add_f32_e32 v133, v133, v155
	v_pk_add_f32 v[102:103], v[102:103], v[158:159] neg_lo:[0,1] neg_hi:[0,1]
	v_add_f32_e32 v133, v133, v148
	v_pk_mul_f32 v[158:159], v[102:103], v[102:103]
	v_add_f32_e32 v133, v133, v149
	v_pk_add_f32 v[104:105], v[104:105], v[152:153] neg_lo:[0,1] neg_hi:[0,1]
	v_add_f32_e32 v133, v133, v158
	v_pk_mul_f32 v[152:153], v[104:105], v[104:105]
	v_add_f32_e32 v133, v133, v159
	v_pk_add_f32 v[106:107], v[106:107], v[162:163] neg_lo:[0,1] neg_hi:[0,1]
	v_add_f32_e32 v133, v133, v152
	v_pk_mul_f32 v[162:163], v[106:107], v[106:107]
	v_add_f32_e32 v133, v133, v153
	v_pk_add_f32 v[108:109], v[108:109], v[156:157] neg_lo:[0,1] neg_hi:[0,1]
	v_add_f32_e32 v133, v133, v162
	v_pk_mul_f32 v[156:157], v[108:109], v[108:109]
	v_add_f32_e32 v133, v133, v163
	v_pk_add_f32 v[110:111], v[110:111], v[166:167] neg_lo:[0,1] neg_hi:[0,1]
	v_add_f32_e32 v133, v133, v156
	v_pk_mul_f32 v[166:167], v[110:111], v[110:111]
	v_add_f32_e32 v133, v133, v157
	v_pk_add_f32 v[112:113], v[112:113], v[160:161] neg_lo:[0,1] neg_hi:[0,1]
	v_add_f32_e32 v133, v133, v166
	v_pk_mul_f32 v[160:161], v[112:113], v[112:113]
	v_add_f32_e32 v133, v133, v167
	v_pk_add_f32 v[114:115], v[114:115], v[170:171] neg_lo:[0,1] neg_hi:[0,1]
	v_add_f32_e32 v133, v133, v160
	v_pk_mul_f32 v[170:171], v[114:115], v[114:115]
	v_add_f32_e32 v133, v133, v161
	v_pk_add_f32 v[84:85], v[84:85], v[164:165] neg_lo:[0,1] neg_hi:[0,1]
	v_add_f32_e32 v133, v133, v170
	v_pk_mul_f32 v[164:165], v[84:85], v[84:85]
	v_add_f32_e32 v133, v133, v171
; DI unsigned pk2(float a, float b) { fl2_t f = {a, b}; bf2_t r = __builtin_convertvector(f, bf2_t); return __builtin_bit_cast(unsigned, r); }
; DI void attn_item(const Params& p, char* lds, int S, const bfr* Qb, const bfr* Kb, const bfr* Vtb, int h, int q0, int tok0) {
;     ...
;         for (int i = 0; i < 16; ++i) { float o = O[t][e][i] - xch[((qg_e * 2 + t) * 64 + e * 16 + i) * 64 + lane_e]; O[t][e][i] = o; ss += o * o; }
;       ss += __shfl_xor(ss, 32, 64);
;       const float rstd = rsqrtf(ss * (1.f / 128.f) + 1e-6f) * 0.8f;
;       bfr* dst = (bfr*)(p.ws + WS_H) + (size_t)(tok0 + q0 + qg_e * 64 + t * 32 + r_e) * D + h * 128;
; #pragma unroll
;       for (int e = 0; e < 4; ++e)
; #pragma unroll
;         for (int g = 0; g < 4; ++g) {
;           const int e0 = e * 32 + 8 * g + 4 * h8_e;
;           float4 gs = *(const float4*)(p.g_subln + e0);
;           u32x2 o;
;           o[0] = pk2(O[t][e][4 * g + 0] * rstd * gs.x, O[t][e][4 * g + 1] * rstd * gs.y);
;           o[1] = pk2(O[t][e][4 * g + 2] * rstd * gs.z, O[t][e][4 * g + 3] * rstd * gs.w);
;           *(u32x2*)(dst + e0) = o;
	v_pk_add_f32 v[86:87], v[86:87], v[174:175] neg_lo:[0,1] neg_hi:[0,1]
	v_add_f32_e32 v133, v133, v164
	v_pk_mul_f32 v[174:175], v[86:87], v[86:87]
	v_add_f32_e32 v133, v133, v165
	v_pk_add_f32 v[88:89], v[88:89], v[168:169] neg_lo:[0,1] neg_hi:[0,1]
	v_add_f32_e32 v133, v133, v174
	v_pk_mul_f32 v[168:169], v[88:89], v[88:89]
	v_add_f32_e32 v133, v133, v175
	v_pk_add_f32 v[90:91], v[90:91], v[178:179] neg_lo:[0,1] neg_hi:[0,1]
	v_add_f32_e32 v133, v133, v168
	v_pk_mul_f32 v[178:179], v[90:91], v[90:91]
	v_add_f32_e32 v133, v133, v169
	v_pk_add_f32 v[92:93], v[92:93], v[172:173] neg_lo:[0,1] neg_hi:[0,1]
	v_add_f32_e32 v133, v133, v178
	v_pk_mul_f32 v[172:173], v[92:93], v[92:93]
	v_add_f32_e32 v133, v133, v179
	v_pk_add_f32 v[94:95], v[94:95], v[182:183] neg_lo:[0,1] neg_hi:[0,1]
	v_add_f32_e32 v133, v133, v172
	v_pk_mul_f32 v[182:183], v[94:95], v[94:95]
	v_add_f32_e32 v133, v133, v173
	v_pk_add_f32 v[96:97], v[96:97], v[176:177] neg_lo:[0,1] neg_hi:[0,1]
	v_add_f32_e32 v133, v133, v182
	v_pk_mul_f32 v[176:177], v[96:97], v[96:97]
	v_add_f32_e32 v133, v133, v183
	v_pk_add_f32 v[98:99], v[98:99], v[186:187] neg_lo:[0,1] neg_hi:[0,1]
	v_add_f32_e32 v133, v133, v176
	v_pk_mul_f32 v[186:187], v[98:99], v[98:99]
	v_add_f32_e32 v133, v133, v177
	v_pk_add_f32 v[180:181], v[68:69], v[180:181] neg_lo:[0,1] neg_hi:[0,1]
	v_add_f32_e32 v133, v133, v186
	v_pk_mul_f32 v[68:69], v[180:181], v[180:181]
	v_add_f32_e32 v133, v133, v187
	v_pk_add_f32 v[188:189], v[70:71], v[188:189] neg_lo:[0,1] neg_hi:[0,1]
	v_add_f32_e32 v68, v133, v68
	v_pk_mul_f32 v[70:71], v[188:189], v[188:189]
	v_add_f32_e32 v68, v68, v69
	v_pk_add_f32 v[184:185], v[72:73], v[184:185] neg_lo:[0,1] neg_hi:[0,1]
	v_add_f32_e32 v68, v68, v70
	v_pk_mul_f32 v[226:227], v[184:185], v[184:185]
	v_add_f32_e32 v68, v68, v71
	v_pk_add_f32 v[190:191], v[74:75], v[190:191] neg_lo:[0,1] neg_hi:[0,1]
	v_add_f32_e32 v68, v68, v226
	v_pk_mul_f32 v[224:225], v[190:191], v[190:191]
	v_add_f32_e32 v68, v68, v227
	s_waitcnt lgkmcnt(2)
	v_pk_add_f32 v[74:75], v[76:77], v[192:193] neg_lo:[0,1] neg_hi:[0,1]
	v_add_f32_e32 v68, v68, v224
	v_pk_mul_f32 v[76:77], v[74:75], v[74:75]
	v_add_f32_e32 v68, v68, v225
	s_waitcnt lgkmcnt(1)
	v_pk_add_f32 v[72:73], v[78:79], v[194:195] neg_lo:[0,1] neg_hi:[0,1]
	v_add_f32_e32 v68, v68, v76
	v_pk_mul_f32 v[78:79], v[72:73], v[72:73]
	v_add_f32_e32 v68, v68, v77
	v_add_f32_e32 v68, v68, v78
	v_pk_mul_f32 v[220:221], v[80:81], v[80:81]
	v_add_f32_e32 v68, v68, v79
	v_add_f32_e32 v68, v68, v220
	v_pk_mul_f32 v[222:223], v[82:83], v[82:83]
	v_add_f32_e32 v68, v68, v221
	v_add_f32_e32 v68, v68, v222
	v_add_f32_e32 v70, v68, v223
	ds_bpermute_b32 v71, v216, v70
	v_ashrrev_i32_e32 v133, 31, v132
	v_lshlrev_b64 v[68:69], 11, v[132:133]
	v_lshl_add_u64 v[68:69], s[22:23], 0, v[68:69]
	s_lshl_b32 s24, s24, 1
	s_waitcnt lgkmcnt(0)
	v_add_f32_e32 v70, v70, v71
	v_fmamk_f32 v70, v70, 0x3c000000, v215
	v_mul_f32_e32 v71, 0x4b800000, v70
	v_cmp_gt_f32_e32 vcc, s40, v70
	v_lshl_add_u64 v[68:69], v[68:69], 0, s[24:25]
	v_lshlrev_b32_e32 v2, 1, v2
	v_cndmask_b32_e32 v70, v70, v71, vcc
	v_rsq_f32_e32 v70, v70
	v_lshl_add_u64 v[68:69], v[68:69], 0, v[2:3]
	v_mov_b32_e32 v152, v135
	v_mov_b32_e32 v153, v200
	v_mul_f32_e32 v71, 0x45800000, v70
	v_cndmask_b32_e32 v70, v70, v71, vcc
	v_mul_f32_e32 v70, 0x3f4ccccd, v70
	v_pk_mul_f32 v[76:77], v[116:117], v[70:71] op_sel_hi:[1,0]
	v_pk_mul_f32 v[78:79], v[118:119], v[70:71] op_sel_hi:[1,0]
	s_waitcnt lgkmcnt(0)
	v_pk_mul_f32 v[76:77], v[196:197], v[76:77]
	v_pk_mul_f32 v[78:79], v[198:199], v[78:79]
	v_cvt_pk_bf16_f32 v76, v76, v77
	v_cvt_pk_bf16_f32 v77, v78, v79
	global_store_dwordx2 v[68:69], v[76:77], off
	ds_read_b128 v[76:79], v255 offset:32
	v_pk_mul_f32 v[116:117], v[120:121], v[70:71] op_sel_hi:[1,0]
	v_pk_mul_f32 v[118:119], v[126:127], v[70:71] op_sel_hi:[1,0]
	v_pk_mul_f32 v[100:101], v[100:101], v[70:71] op_sel_hi:[1,0]
	v_pk_mul_f32 v[102:103], v[102:103], v[70:71] op_sel_hi:[1,0]
	v_pk_mul_f32 v[84:85], v[84:85], v[70:71] op_sel_hi:[1,0]
	v_pk_mul_f32 v[86:87], v[86:87], v[70:71] op_sel_hi:[1,0]
	v_pk_add_f32 v[52:53], v[52:53], v[152:153] neg_lo:[0,1] neg_hi:[0,1]
	s_waitcnt lgkmcnt(0)
	v_pk_mul_f32 v[76:77], v[76:77], v[116:117]
	v_pk_mul_f32 v[116:117], v[122:123], v[70:71] op_sel_hi:[1,0]
	v_cvt_pk_bf16_f32 v76, v76, v77
	v_pk_mul_f32 v[78:79], v[78:79], v[116:117]
	v_pk_mul_f32 v[116:117], v[124:125], v[70:71] op_sel_hi:[1,0]
	v_cvt_pk_bf16_f32 v77, v78, v79
	global_store_dwordx2 v[68:69], v[76:77], off offset:16
	ds_read_b128 v[76:79], v255 offset:64
	s_waitcnt lgkmcnt(0)
	v_pk_mul_f32 v[76:77], v[116:117], v[76:77]
	v_pk_mul_f32 v[78:79], v[118:119], v[78:79]
	v_cvt_pk_bf16_f32 v76, v76, v77
	v_cvt_pk_bf16_f32 v77, v78, v79
	global_store_dwordx2 v[68:69], v[76:77], off offset:32
	ds_read_b128 v[76:79], v255 offset:96
	v_pk_mul_f32 v[116:117], v[128:129], v[70:71] op_sel_hi:[1,0]
	v_pk_mul_f32 v[118:119], v[130:131], v[70:71] op_sel_hi:[1,0]
	s_waitcnt lgkmcnt(0)
	v_pk_mul_f32 v[76:77], v[116:117], v[76:77]
	v_pk_mul_f32 v[78:79], v[118:119], v[78:79]
	v_cvt_pk_bf16_f32 v76, v76, v77
	v_cvt_pk_bf16_f32 v77, v78, v79
	global_store_dwordx2 v[68:69], v[76:77], off offset:48
	ds_read_b128 v[76:79], v255 offset:128
	s_waitcnt lgkmcnt(0)
	v_pk_mul_f32 v[76:77], v[100:101], v[76:77]
	v_pk_mul_f32 v[78:79], v[102:103], v[78:79]
	v_cvt_pk_bf16_f32 v76, v76, v77
	v_cvt_pk_bf16_f32 v77, v78, v79
	global_store_dwordx2 v[68:69], v[76:77], off offset:64
	ds_read_b128 v[76:79], v255 offset:160
	v_pk_mul_f32 v[100:101], v[104:105], v[70:71] op_sel_hi:[1,0]
	v_pk_mul_f32 v[102:103], v[106:107], v[70:71] op_sel_hi:[1,0]
	s_waitcnt lgkmcnt(0)
; DI unsigned pk2(float a, float b) { fl2_t f = {a, b}; bf2_t r = __builtin_convertvector(f, bf2_t); return __builtin_bit_cast(unsigned, r); }
; DI void attn_item(const Params& p, char* lds, int S, const bfr* Qb, const bfr* Kb, const bfr* Vtb, int h, int q0, int tok0) {
;     ...
;       bfr* dst = (bfr*)(p.ws + WS_H) + (size_t)(tok0 + q0 + qg_e * 64 + t * 32 + r_e) * D + h * 128;
; #pragma unroll
;       for (int e = 0; e < 4; ++e)
; #pragma unroll
;         for (int g = 0; g < 4; ++g) {
;           const int e0 = e * 32 + 8 * g + 4 * h8_e;
;           float4 gs = *(const float4*)(p.g_subln + e0);
;           u32x2 o;
;           o[0] = pk2(O[t][e][4 * g + 0] * rstd * gs.x, O[t][e][4 * g + 1] * rstd * gs.y);
;           o[1] = pk2(O[t][e][4 * g + 2] * rstd * gs.z, O[t][e][4 * g + 3] * rstd * gs.w);
;           *(u32x2*)(dst + e0) = o;
;         }
	v_pk_mul_f32 v[76:77], v[100:101], v[76:77]
	v_pk_mul_f32 v[78:79], v[102:103], v[78:79]
	v_cvt_pk_bf16_f32 v76, v76, v77
	v_cvt_pk_bf16_f32 v77, v78, v79
	global_store_dwordx2 v[68:69], v[76:77], off offset:80
	ds_read_b128 v[76:79], v255 offset:192
	v_pk_mul_f32 v[100:101], v[108:109], v[70:71] op_sel_hi:[1,0]
	v_pk_mul_f32 v[102:103], v[110:111], v[70:71] op_sel_hi:[1,0]
	s_waitcnt lgkmcnt(0)
	v_pk_mul_f32 v[76:77], v[100:101], v[76:77]
	v_pk_mul_f32 v[78:79], v[102:103], v[78:79]
	v_cvt_pk_bf16_f32 v76, v76, v77
	v_cvt_pk_bf16_f32 v77, v78, v79
	global_store_dwordx2 v[68:69], v[76:77], off offset:96
	ds_read_b128 v[76:79], v255 offset:224
	v_pk_mul_f32 v[100:101], v[112:113], v[70:71] op_sel_hi:[1,0]
	v_pk_mul_f32 v[102:103], v[114:115], v[70:71] op_sel_hi:[1,0]
	s_waitcnt lgkmcnt(0)
	v_pk_mul_f32 v[76:77], v[100:101], v[76:77]
	v_pk_mul_f32 v[78:79], v[102:103], v[78:79]
	v_cvt_pk_bf16_f32 v76, v76, v77
	v_cvt_pk_bf16_f32 v77, v78, v79
	global_store_dwordx2 v[68:69], v[76:77], off offset:112
	ds_read_b128 v[76:79], v255 offset:256
	v_pk_mul_f32 v[100:101], v[184:185], v[70:71] op_sel_hi:[1,0]
	v_pk_mul_f32 v[102:103], v[190:191], v[70:71] op_sel_hi:[1,0]
	s_waitcnt lgkmcnt(0)
	v_pk_mul_f32 v[76:77], v[84:85], v[76:77]
	v_pk_mul_f32 v[78:79], v[86:87], v[78:79]
	v_cvt_pk_bf16_f32 v76, v76, v77
	v_cvt_pk_bf16_f32 v77, v78, v79
	global_store_dwordx2 v[68:69], v[76:77], off offset:128
	ds_read_b128 v[76:79], v255 offset:288
	v_pk_mul_f32 v[84:85], v[88:89], v[70:71] op_sel_hi:[1,0]
	v_pk_mul_f32 v[86:87], v[90:91], v[70:71] op_sel_hi:[1,0]
	s_waitcnt lgkmcnt(0)
	v_pk_mul_f32 v[76:77], v[84:85], v[76:77]
	v_pk_mul_f32 v[78:79], v[86:87], v[78:79]
	v_cvt_pk_bf16_f32 v76, v76, v77
	v_cvt_pk_bf16_f32 v77, v78, v79
	global_store_dwordx2 v[68:69], v[76:77], off offset:144
	ds_read_b128 v[76:79], v255 offset:320
	v_pk_mul_f32 v[84:85], v[92:93], v[70:71] op_sel_hi:[1,0]
	v_pk_mul_f32 v[86:87], v[94:95], v[70:71] op_sel_hi:[1,0]
	s_waitcnt lgkmcnt(0)
	v_pk_mul_f32 v[76:77], v[84:85], v[76:77]
	v_pk_mul_f32 v[78:79], v[86:87], v[78:79]
	v_cvt_pk_bf16_f32 v76, v76, v77
	v_cvt_pk_bf16_f32 v77, v78, v79
	global_store_dwordx2 v[68:69], v[76:77], off offset:160
	ds_read_b128 v[76:79], v255 offset:352
	v_pk_mul_f32 v[84:85], v[96:97], v[70:71] op_sel_hi:[1,0]
	v_pk_mul_f32 v[86:87], v[98:99], v[70:71] op_sel_hi:[1,0]
	s_waitcnt lgkmcnt(0)
	v_pk_mul_f32 v[76:77], v[84:85], v[76:77]
	v_pk_mul_f32 v[78:79], v[86:87], v[78:79]
	v_cvt_pk_bf16_f32 v76, v76, v77
	v_cvt_pk_bf16_f32 v77, v78, v79
	global_store_dwordx2 v[68:69], v[76:77], off offset:176
	ds_read_b128 v[76:79], v255 offset:384
	v_pk_mul_f32 v[84:85], v[180:181], v[70:71] op_sel_hi:[1,0]
	v_pk_mul_f32 v[86:87], v[188:189], v[70:71] op_sel_hi:[1,0]
	v_or_b32_e32 v71, 0x7f00, v218
	v_pk_mul_f32 v[74:75], v[74:75], v[70:71] op_sel_hi:[1,0]
	v_pk_mul_f32 v[72:73], v[72:73], v[70:71] op_sel_hi:[1,0]
	s_waitcnt lgkmcnt(0)
	v_pk_mul_f32 v[76:77], v[84:85], v[76:77]
	v_pk_mul_f32 v[78:79], v[86:87], v[78:79]
	v_cvt_pk_bf16_f32 v76, v76, v77
	v_cvt_pk_bf16_f32 v77, v78, v79
	global_store_dwordx2 v[68:69], v[76:77], off offset:192
	ds_read_b128 v[76:79], v255 offset:416
	ds_read2st64_b32 v[84:85], v217 offset0:67 offset1:68
	ds_read2st64_b32 v[86:87], v217 offset0:69 offset1:70
	ds_read2st64_b32 v[88:89], v217 offset0:71 offset1:72
	ds_read2st64_b32 v[90:91], v217 offset0:73 offset1:74
	ds_read2st64_b32 v[92:93], v217 offset0:75 offset1:76
	ds_read2st64_b32 v[94:95], v217 offset0:77 offset1:78
	ds_read2st64_b32 v[96:97], v217 offset0:79 offset1:80
	ds_read2st64_b32 v[98:99], v217 offset0:81 offset1:82
	s_waitcnt lgkmcnt(5)
	v_mov_b32_e32 v155, v88
	v_mov_b32_e32 v88, v89
	s_waitcnt lgkmcnt(4)
	v_mov_b32_e32 v89, v90
	s_waitcnt lgkmcnt(2)
	v_mov_b32_e32 v90, v95
	v_mov_b32_e32 v154, v87
	v_mov_b32_e32 v87, v92
	v_mov_b32_e32 v92, v93
	v_mov_b32_e32 v93, v94
	s_waitcnt lgkmcnt(0)
	v_mov_b32_e32 v94, v99
	v_pk_add_f32 v[58:59], v[58:59], v[154:155] neg_lo:[0,1] neg_hi:[0,1]
	v_pk_add_f32 v[60:61], v[60:61], v[88:89] neg_lo:[0,1] neg_hi:[0,1]
	v_pk_add_f32 v[64:65], v[64:65], v[92:93] neg_lo:[0,1] neg_hi:[0,1]
	s_waitcnt lgkmcnt(0)
	v_pk_mul_f32 v[76:77], v[100:101], v[76:77]
	v_pk_mul_f32 v[78:79], v[102:103], v[78:79]
	v_cvt_pk_bf16_f32 v76, v76, v77
	v_cvt_pk_bf16_f32 v77, v78, v79
	global_store_dwordx2 v[68:69], v[76:77], off offset:208
	ds_read_b128 v[76:79], v255 offset:448
	ds_read2st64_b32 v[100:101], v217 offset0:83 offset1:84
	ds_read2st64_b32 v[102:103], v217 offset0:85 offset1:86
	ds_read2st64_b32 v[104:105], v217 offset0:87 offset1:88
	ds_read2st64_b32 v[106:107], v217 offset0:89 offset1:90
	ds_read2st64_b32 v[108:109], v217 offset0:91 offset1:92
	ds_read2st64_b32 v[110:111], v217 offset0:93 offset1:94
	ds_read2st64_b32 v[112:113], v217 offset0:95 offset1:96
	ds_read2st64_b32 v[114:115], v217 offset0:97 offset1:98
	ds_read2st64_b32 v[116:117], v217 offset0:99 offset1:100
	ds_read2st64_b32 v[118:119], v217 offset0:101 offset1:102
	ds_read2st64_b32 v[120:121], v217 offset0:103 offset1:104
	ds_read2st64_b32 v[122:123], v217 offset0:105 offset1:106
	ds_read2st64_b32 v[124:125], v217 offset0:107 offset1:108
	ds_read2st64_b32 v[126:127], v217 offset0:109 offset1:110
	ds_read2st64_b32 v[128:129], v217 offset0:111 offset1:112
	ds_read2st64_b32 v[130:131], v217 offset0:113 offset1:114
	ds_read2st64_b32 v[136:137], v217 offset0:123 offset1:124
	ds_read2st64_b32 v[138:139], v217 offset0:125 offset1:126
	ds_read2st64_b32 v[140:141], v217 offset0:115 offset1:116
	ds_read2st64_b32 v[142:143], v217 offset0:117 offset1:118
	ds_read2st64_b32 v[144:145], v217 offset0:119 offset1:120
	ds_read2st64_b32 v[146:147], v217 offset0:121 offset1:122
	ds_read_b32 v149, v71
	s_waitcnt lgkmcnt(5)
; DI unsigned pk2(float a, float b) { fl2_t f = {a, b}; bf2_t r = __builtin_convertvector(f, bf2_t); return __builtin_bit_cast(unsigned, r); }
; DI void attn_item(const Params& p, char* lds, int S, const bfr* Qb, const bfr* Kb, const bfr* Vtb, int h, int q0, int tok0) {
;     ...
;         for (int i = 0; i < 16; ++i) { float o = O[t][e][i] - xch[((qg_e * 2 + t) * 64 + e * 16 + i) * 64 + lane_e]; O[t][e][i] = o; ss += o * o; }
;       ss += __shfl_xor(ss, 32, 64);
;       const float rstd = rsqrtf(ss * (1.f / 128.f) + 1e-6f) * 0.8f;
;       bfr* dst = (bfr*)(p.ws + WS_H) + (size_t)(tok0 + q0 + qg_e * 64 + t * 32 + r_e) * D + h * 128;
; #pragma unroll
;       for (int e = 0; e < 4; ++e)
; #pragma unroll
;         for (int g = 0; g < 4; ++g) {
;           const int e0 = e * 32 + 8 * g + 4 * h8_e;
;           float4 gs = *(const float4*)(p.g_subln + e0);
;           u32x2 o;
;           o[0] = pk2(O[t][e][4 * g + 0] * rstd * gs.x, O[t][e][4 * g + 1] * rstd * gs.y);
;           o[1] = pk2(O[t][e][4 * g + 2] * rstd * gs.z, O[t][e][4 * g + 3] * rstd * gs.w);
;           *(u32x2*)(dst + e0) = o;
;         }
	v_mov_b32_e32 v151, v138
	v_mov_b32_e32 v148, v139
	v_mov_b32_e32 v138, v201
	v_mov_b32_e32 v139, v84
	v_mov_b32_e32 v84, v85
	v_mov_b32_e32 v85, v86
	v_mov_b32_e32 v86, v91
	v_mov_b32_e32 v91, v96
	v_mov_b32_e32 v95, v100
	v_mov_b32_e32 v96, v97
	v_mov_b32_e32 v97, v98
	v_mov_b32_e32 v98, v103
	v_mov_b32_e32 v100, v101
	v_mov_b32_e32 v101, v102
	v_mov_b32_e32 v102, v107
	v_mov_b32_e32 v103, v108
	v_mov_b32_e32 v107, v112
	v_mov_b32_e32 v108, v109
	v_mov_b32_e32 v109, v110
	v_mov_b32_e32 v110, v115
	v_mov_b32_e32 v112, v113
	v_mov_b32_e32 v113, v114
	v_mov_b32_e32 v115, v120
	v_mov_b32_e32 v120, v121
	v_mov_b32_e32 v121, v122
	v_mov_b32_e32 v122, v127
	s_waitcnt lgkmcnt(4)
	v_mov_b32_e32 v127, v140
	s_waitcnt lgkmcnt(1)
	v_mov_b32_e32 v140, v147
	v_mov_b32_e32 v150, v137
	v_mov_b32_e32 v114, v119
	v_mov_b32_e32 v119, v124
	v_mov_b32_e32 v124, v125
	v_mov_b32_e32 v125, v126
	v_mov_b32_e32 v126, v131
	v_mov_b32_e32 v137, v146
	v_pk_add_f32 v[54:55], v[54:55], v[138:139] neg_lo:[0,1] neg_hi:[0,1]
	v_pk_add_f32 v[66:67], v[66:67], v[90:91] neg_lo:[0,1] neg_hi:[0,1]
	v_pk_add_f32 v[90:91], v[20:21], v[112:113] neg_lo:[0,1] neg_hi:[0,1]
	v_pk_add_f32 v[56:57], v[56:57], v[84:85] neg_lo:[0,1] neg_hi:[0,1]
	v_mov_b32_e32 v99, v104
	v_mov_b32_e32 v104, v105
	v_mov_b32_e32 v105, v106
	v_mov_b32_e32 v106, v111
	v_mov_b32_e32 v111, v116
	v_mov_b32_e32 v116, v117
	v_mov_b32_e32 v117, v118
	v_mov_b32_e32 v118, v123
	v_mov_b32_e32 v123, v128
	v_pk_add_f32 v[88:89], v[22:23], v[110:111] neg_lo:[0,1] neg_hi:[0,1]
	v_pk_add_f32 v[22:23], v[34:35], v[122:123] neg_lo:[0,1] neg_hi:[0,1]
	v_pk_mul_f32 v[34:35], v[58:59], v[58:59]
	v_pk_add_f32 v[84:85], v[38:39], v[94:95] neg_lo:[0,1] neg_hi:[0,1]
	v_pk_mul_f32 v[94:95], v[60:61], v[60:61]
	v_pk_add_f32 v[62:63], v[62:63], v[86:87] neg_lo:[0,1] neg_hi:[0,1]
	v_pk_add_f32 v[42:43], v[42:43], v[98:99] neg_lo:[0,1] neg_hi:[0,1]
	v_pk_mul_f32 v[92:93], v[62:63], v[62:63]
	v_pk_mul_f32 v[98:99], v[64:65], v[64:65]
	v_pk_add_f32 v[86:87], v[36:37], v[96:97] neg_lo:[0,1] neg_hi:[0,1]
	v_pk_mul_f32 v[96:97], v[66:67], v[66:67]
	v_pk_add_f32 v[46:47], v[46:47], v[102:103] neg_lo:[0,1] neg_hi:[0,1]
	v_pk_mul_f32 v[102:103], v[86:87], v[86:87]
	v_pk_add_f32 v[40:41], v[40:41], v[100:101] neg_lo:[0,1] neg_hi:[0,1]
	v_pk_mul_f32 v[100:101], v[84:85], v[84:85]
	v_pk_add_f32 v[50:51], v[50:51], v[106:107] neg_lo:[0,1] neg_hi:[0,1]
	v_pk_mul_f32 v[106:107], v[40:41], v[40:41]
	v_pk_add_f32 v[44:45], v[44:45], v[104:105] neg_lo:[0,1] neg_hi:[0,1]
	v_pk_mul_f32 v[104:105], v[42:43], v[42:43]
	v_pk_mul_f32 v[110:111], v[44:45], v[44:45]
	v_pk_add_f32 v[48:49], v[48:49], v[108:109] neg_lo:[0,1] neg_hi:[0,1]
	v_pk_mul_f32 v[108:109], v[46:47], v[46:47]
	v_pk_add_f32 v[36:37], v[26:27], v[114:115] neg_lo:[0,1] neg_hi:[0,1]
	v_pk_mul_f32 v[114:115], v[48:49], v[48:49]
	v_pk_mul_f32 v[112:113], v[50:51], v[50:51]
	v_pk_add_f32 v[26:27], v[30:31], v[118:119] neg_lo:[0,1] neg_hi:[0,1]
	v_pk_mul_f32 v[118:119], v[90:91], v[90:91]
	v_pk_add_f32 v[38:39], v[24:25], v[116:117] neg_lo:[0,1] neg_hi:[0,1]
	v_pk_mul_f32 v[116:117], v[88:89], v[88:89]
	s_waitcnt lgkmcnt(0)
	v_pk_mul_f32 v[74:75], v[74:75], v[76:77]
	v_pk_mul_f32 v[72:73], v[72:73], v[78:79]
	v_cvt_pk_bf16_f32 v74, v74, v75
	v_cvt_pk_bf16_f32 v75, v72, v73
	global_store_dwordx2 v[68:69], v[74:75], off offset:224
	ds_read_b128 v[74:77], v255 offset:480
	v_mov_b32_e32 v78, v129
	v_mov_b32_e32 v79, v130
	v_mov_b32_e32 v130, v141
	v_mov_b32_e32 v141, v136
	v_mov_b32_e32 v136, v145
	v_pk_add_f32 v[20:21], v[4:5], v[78:79] neg_lo:[0,1] neg_hi:[0,1]
	v_pk_add_f32 v[4:5], v[14:15], v[140:141] neg_lo:[0,1] neg_hi:[0,1]
	v_pk_mul_f32 v[14:15], v[52:53], v[52:53]
	v_pk_add_f32 v[72:73], v[16:17], v[150:151] neg_lo:[0,1] neg_hi:[0,1]
	s_waitcnt lgkmcnt(0)
	v_pk_add_f32 v[16:17], v[18:19], v[148:149] neg_lo:[0,1] neg_hi:[0,1]
	v_pk_add_f32 v[18:19], v[6:7], v[126:127] neg_lo:[0,1] neg_hi:[0,1]
	v_pk_add_f32 v[6:7], v[12:13], v[136:137] neg_lo:[0,1] neg_hi:[0,1]
	v_pk_mul_f32 v[12:13], v[54:55], v[54:55]
	v_add_f32_e32 v14, v14, v15
	v_add_f32_e32 v12, v14, v12
	v_add_f32_e32 v71, v12, v13
	v_pk_mul_f32 v[12:13], v[80:81], v[70:71] op_sel_hi:[1,0]
	v_pk_mul_f32 v[14:15], v[82:83], v[70:71] op_sel_hi:[1,0]
	v_pk_mul_f32 v[78:79], v[56:57], v[56:57]
	v_pk_mul_f32 v[122:123], v[38:39], v[38:39]
	v_pk_add_f32 v[28:29], v[28:29], v[120:121] neg_lo:[0,1] neg_hi:[0,1]
	v_pk_mul_f32 v[120:121], v[36:37], v[36:37]
	v_pk_mul_f32 v[126:127], v[28:29], v[28:29]
	v_pk_add_f32 v[24:25], v[32:33], v[124:125] neg_lo:[0,1] neg_hi:[0,1]
	v_pk_mul_f32 v[124:125], v[26:27], v[26:27]
	v_mov_b32_e32 v131, v142
	v_pk_add_f32 v[8:9], v[8:9], v[130:131] neg_lo:[0,1] neg_hi:[0,1]
	v_pk_mul_f32 v[130:131], v[24:25], v[24:25]
	v_mov_b32_e32 v128, v143
	v_mov_b32_e32 v129, v144
	v_pk_add_f32 v[10:11], v[10:11], v[128:129] neg_lo:[0,1] neg_hi:[0,1]
	v_pk_mul_f32 v[128:129], v[22:23], v[22:23]
	v_pk_mul_f32 v[138:139], v[20:21], v[20:21]
	v_pk_mul_f32 v[136:137], v[18:19], v[18:19]
	v_pk_mul_f32 v[142:143], v[8:9], v[8:9]
	v_pk_mul_f32 v[140:141], v[10:11], v[10:11]
	v_pk_mul_f32 v[146:147], v[6:7], v[6:7]
	v_pk_mul_f32 v[144:145], v[4:5], v[4:5]
	v_pk_mul_f32 v[30:31], v[72:73], v[72:73]
	v_pk_mul_f32 v[32:33], v[16:17], v[16:17]
	s_waitcnt lgkmcnt(0)
; DI unsigned pk2(float a, float b) { fl2_t f = {a, b}; bf2_t r = __builtin_convertvector(f, bf2_t); return __builtin_bit_cast(unsigned, r); }
; DI void attn_item(const Params& p, char* lds, int S, const bfr* Qb, const bfr* Kb, const bfr* Vtb, int h, int q0, int tok0) {
;     ...
;         for (int i = 0; i < 16; ++i) { float o = O[t][e][i] - xch[((qg_e * 2 + t) * 64 + e * 16 + i) * 64 + lane_e]; O[t][e][i] = o; ss += o * o; }
;       ss += __shfl_xor(ss, 32, 64);
;       const float rstd = rsqrtf(ss * (1.f / 128.f) + 1e-6f) * 0.8f;
;       bfr* dst = (bfr*)(p.ws + WS_H) + (size_t)(tok0 + q0 + qg_e * 64 + t * 32 + r_e) * D + h * 128;
; #pragma unroll
;       for (int e = 0; e < 4; ++e)
; #pragma unroll
;         for (int g = 0; g < 4; ++g) {
;           const int e0 = e * 32 + 8 * g + 4 * h8_e;
;           float4 gs = *(const float4*)(p.g_subln + e0);
;           u32x2 o;
;           o[0] = pk2(O[t][e][4 * g + 0] * rstd * gs.x, O[t][e][4 * g + 1] * rstd * gs.y);
;           o[1] = pk2(O[t][e][4 * g + 2] * rstd * gs.z, O[t][e][4 * g + 3] * rstd * gs.w);
;           *(u32x2*)(dst + e0) = o;
	v_pk_mul_f32 v[12:13], v[12:13], v[74:75]
	v_pk_mul_f32 v[14:15], v[14:15], v[76:77]
	v_cvt_pk_bf16_f32 v12, v12, v13
	v_cvt_pk_bf16_f32 v13, v14, v15
	global_store_dwordx2 v[68:69], v[12:13], off offset:240
	ds_read_b128 v[12:15], v255
	v_add_f32_e32 v68, v71, v78
	v_add_f32_e32 v68, v68, v79
	v_add_f32_e32 v34, v68, v34
	v_add_f32_e32 v34, v34, v35
	v_add_f32_e32 v34, v34, v94
	v_add_f32_e32 v34, v34, v95
	v_add_f32_e32 v34, v34, v92
	v_add_f32_e32 v34, v34, v93
	v_add_f32_e32 v34, v34, v98
	v_add_f32_e32 v34, v34, v99
	v_add_f32_e32 v34, v34, v96
	v_add_f32_e32 v34, v34, v97
	v_add_f32_e32 v34, v34, v102
	v_add_f32_e32 v34, v34, v103
	v_add_f32_e32 v34, v34, v100
	v_add_f32_e32 v34, v34, v101
	v_add_f32_e32 v34, v34, v106
	v_add_f32_e32 v34, v34, v107
	v_add_f32_e32 v34, v34, v104
	v_add_f32_e32 v34, v34, v105
	v_add_f32_e32 v34, v34, v110
	v_add_f32_e32 v34, v34, v111
	v_add_f32_e32 v34, v34, v108
	v_add_f32_e32 v34, v34, v109
	v_add_f32_e32 v34, v34, v114
	v_add_f32_e32 v34, v34, v115
	v_add_f32_e32 v34, v34, v112
	v_add_f32_e32 v34, v34, v113
	v_add_f32_e32 v34, v34, v118
	v_add_f32_e32 v34, v34, v119
	v_add_f32_e32 v34, v34, v116
	v_add_f32_e32 v34, v34, v117
	v_add_f32_e32 v34, v34, v122
	v_add_f32_e32 v34, v34, v123
	v_add_f32_e32 v34, v34, v120
	v_add_f32_e32 v34, v34, v121
	v_add_f32_e32 v34, v34, v126
	v_add_f32_e32 v34, v34, v127
	v_add_f32_e32 v34, v34, v124
	v_add_f32_e32 v34, v34, v125
	v_add_f32_e32 v34, v34, v130
	v_add_f32_e32 v34, v34, v131
	v_add_f32_e32 v34, v34, v128
	v_add_f32_e32 v34, v34, v129
	v_add_f32_e32 v34, v34, v138
	v_add_f32_e32 v34, v34, v139
	v_add_f32_e32 v34, v34, v136
	v_add_f32_e32 v34, v34, v137
	v_add_f32_e32 v34, v34, v142
	v_add_f32_e32 v34, v34, v143
	v_add_f32_e32 v34, v34, v140
	v_add_f32_e32 v34, v34, v141
	v_add_f32_e32 v34, v34, v146
	v_add_f32_e32 v34, v34, v147
	v_add_f32_e32 v34, v34, v144
	v_add_f32_e32 v34, v34, v145
	v_add_f32_e32 v30, v34, v30
	v_add_f32_e32 v30, v30, v31
	v_add_f32_e32 v30, v30, v32
	v_add_f32_e32 v32, v30, v33
	ds_bpermute_b32 v33, v216, v32
	v_add_u32_e32 v30, 32, v132
	v_ashrrev_i32_e32 v31, 31, v30
	v_lshlrev_b64 v[30:31], 11, v[30:31]
	v_lshl_add_u64 v[30:31], s[22:23], 0, v[30:31]
	s_waitcnt lgkmcnt(0)
	v_add_f32_e32 v32, v32, v33
	v_fmamk_f32 v32, v32, 0x3c000000, v215
	v_mul_f32_e32 v33, 0x4b800000, v32
	v_cmp_gt_f32_e32 vcc, s40, v32
	v_lshl_add_u64 v[30:31], v[30:31], 0, s[24:25]
	v_lshl_add_u64 v[30:31], v[30:31], 0, v[2:3]
	v_cndmask_b32_e32 v32, v32, v33, vcc
	v_rsq_f32_e32 v32, v32
	s_nop 0
	v_mul_f32_e32 v2, 0x45800000, v32
	v_cndmask_b32_e32 v2, v32, v2, vcc
	v_mul_f32_e32 v2, 0x3f4ccccd, v2
	v_pk_mul_f32 v[32:33], v[52:53], v[2:3] op_sel_hi:[1,0]
	v_pk_mul_f32 v[34:35], v[54:55], v[2:3] op_sel_hi:[1,0]
	s_waitcnt lgkmcnt(0)
	v_pk_mul_f32 v[12:13], v[12:13], v[32:33]
	v_pk_mul_f32 v[14:15], v[14:15], v[34:35]
	v_cvt_pk_bf16_f32 v12, v12, v13
	v_cvt_pk_bf16_f32 v13, v14, v15
	global_store_dwordx2 v[30:31], v[12:13], off
	ds_read_b128 v[12:15], v255 offset:32
	v_pk_mul_f32 v[32:33], v[56:57], v[2:3] op_sel_hi:[1,0]
	v_pk_mul_f32 v[34:35], v[58:59], v[2:3] op_sel_hi:[1,0]
	v_pk_mul_f32 v[28:29], v[28:29], v[2:3] op_sel_hi:[1,0]
	v_pk_mul_f32 v[26:27], v[26:27], v[2:3] op_sel_hi:[1,0]
	v_pk_mul_f32 v[24:25], v[24:25], v[2:3] op_sel_hi:[1,0]
	v_pk_mul_f32 v[22:23], v[22:23], v[2:3] op_sel_hi:[1,0]
	v_pk_mul_f32 v[20:21], v[20:21], v[2:3] op_sel_hi:[1,0]
	v_pk_mul_f32 v[18:19], v[18:19], v[2:3] op_sel_hi:[1,0]
	v_pk_mul_f32 v[8:9], v[8:9], v[2:3] op_sel_hi:[1,0]
	v_pk_mul_f32 v[10:11], v[10:11], v[2:3] op_sel_hi:[1,0]
	v_pk_mul_f32 v[6:7], v[6:7], v[2:3] op_sel_hi:[1,0]
	v_pk_mul_f32 v[4:5], v[4:5], v[2:3] op_sel_hi:[1,0]
	s_waitcnt lgkmcnt(0)
	v_pk_mul_f32 v[12:13], v[12:13], v[32:33]
	v_pk_mul_f32 v[14:15], v[14:15], v[34:35]
	v_cvt_pk_bf16_f32 v12, v12, v13
	v_cvt_pk_bf16_f32 v13, v14, v15
	global_store_dwordx2 v[30:31], v[12:13], off offset:16
	ds_read_b128 v[12:15], v255 offset:64
	v_pk_mul_f32 v[32:33], v[60:61], v[2:3] op_sel_hi:[1,0]
	v_pk_mul_f32 v[34:35], v[62:63], v[2:3] op_sel_hi:[1,0]
	s_waitcnt lgkmcnt(0)
	v_pk_mul_f32 v[12:13], v[32:33], v[12:13]
	v_pk_mul_f32 v[14:15], v[34:35], v[14:15]
	v_cvt_pk_bf16_f32 v12, v12, v13
	v_cvt_pk_bf16_f32 v13, v14, v15
	global_store_dwordx2 v[30:31], v[12:13], off offset:32
	ds_read_b128 v[12:15], v255 offset:96
	v_pk_mul_f32 v[32:33], v[64:65], v[2:3] op_sel_hi:[1,0]
	v_pk_mul_f32 v[34:35], v[66:67], v[2:3] op_sel_hi:[1,0]
	s_waitcnt lgkmcnt(0)
; DI unsigned pk2(float a, float b) { fl2_t f = {a, b}; bf2_t r = __builtin_convertvector(f, bf2_t); return __builtin_bit_cast(unsigned, r); }
; #define WAIT_V(n) asm volatile("s_waitcnt vmcnt(%0)" ::"n"(n) : "memory")
; #define RAW_BARRIER() do { asm volatile("s_waitcnt lgkmcnt(0)" ::: "memory"); __builtin_amdgcn_s_barrier(); } while (0)
; DI void attn_item(const Params& p, char* lds, int S, const bfr* Qb, const bfr* Kb, const bfr* Vtb, int h, int q0, int tok0) {
;     ...
;   for (int kt = 0; kt < nkt; ++kt) {
;     if (kt + 2 < nkt) WAIT_V(4); else if (kt + 1 < nkt) WAIT_V(2); else WAIT_V(0);
;     RAW_BARRIER();
;     if (kt + 3 < nkt) stage((kt + 3) & 3, kt + 3);
;     ...
;       bfr* dst = (bfr*)(p.ws + WS_H) + (size_t)(tok0 + q0 + qg_e * 64 + t * 32 + r_e) * D + h * 128;
; #pragma unroll
;       for (int e = 0; e < 4; ++e)
; #pragma unroll
;         for (int g = 0; g < 4; ++g) {
;           const int e0 = e * 32 + 8 * g + 4 * h8_e;
;           float4 gs = *(const float4*)(p.g_subln + e0);
;           u32x2 o;
;           o[0] = pk2(O[t][e][4 * g + 0] * rstd * gs.x, O[t][e][4 * g + 1] * rstd * gs.y);
;           o[1] = pk2(O[t][e][4 * g + 2] * rstd * gs.z, O[t][e][4 * g + 3] * rstd * gs.w);
;           *(u32x2*)(dst + e0) = o;
;         }
	v_pk_mul_f32 v[12:13], v[32:33], v[12:13]
	v_pk_mul_f32 v[14:15], v[34:35], v[14:15]
	v_cvt_pk_bf16_f32 v12, v12, v13
	v_cvt_pk_bf16_f32 v13, v14, v15
	global_store_dwordx2 v[30:31], v[12:13], off offset:48
	ds_read_b128 v[12:15], v255 offset:128
	v_pk_mul_f32 v[32:33], v[86:87], v[2:3] op_sel_hi:[1,0]
	v_pk_mul_f32 v[34:35], v[84:85], v[2:3] op_sel_hi:[1,0]
	s_waitcnt lgkmcnt(0)
	v_pk_mul_f32 v[12:13], v[32:33], v[12:13]
	v_pk_mul_f32 v[14:15], v[34:35], v[14:15]
	v_cvt_pk_bf16_f32 v12, v12, v13
	v_cvt_pk_bf16_f32 v13, v14, v15
	global_store_dwordx2 v[30:31], v[12:13], off offset:64
	ds_read_b128 v[12:15], v255 offset:160
	v_pk_mul_f32 v[32:33], v[40:41], v[2:3] op_sel_hi:[1,0]
	v_pk_mul_f32 v[34:35], v[42:43], v[2:3] op_sel_hi:[1,0]
	s_waitcnt lgkmcnt(0)
	v_pk_mul_f32 v[12:13], v[32:33], v[12:13]
	v_pk_mul_f32 v[14:15], v[34:35], v[14:15]
	v_cvt_pk_bf16_f32 v12, v12, v13
	v_cvt_pk_bf16_f32 v13, v14, v15
	global_store_dwordx2 v[30:31], v[12:13], off offset:80
	ds_read_b128 v[12:15], v255 offset:192
	v_pk_mul_f32 v[32:33], v[44:45], v[2:3] op_sel_hi:[1,0]
	v_pk_mul_f32 v[34:35], v[46:47], v[2:3] op_sel_hi:[1,0]
	s_waitcnt lgkmcnt(0)
	v_pk_mul_f32 v[12:13], v[32:33], v[12:13]
	v_pk_mul_f32 v[14:15], v[34:35], v[14:15]
	v_cvt_pk_bf16_f32 v12, v12, v13
	v_cvt_pk_bf16_f32 v13, v14, v15
	global_store_dwordx2 v[30:31], v[12:13], off offset:96
	ds_read_b128 v[12:15], v255 offset:224
	v_pk_mul_f32 v[32:33], v[48:49], v[2:3] op_sel_hi:[1,0]
	v_pk_mul_f32 v[34:35], v[50:51], v[2:3] op_sel_hi:[1,0]
	s_waitcnt lgkmcnt(0)
	v_pk_mul_f32 v[12:13], v[32:33], v[12:13]
	v_pk_mul_f32 v[14:15], v[34:35], v[14:15]
	v_cvt_pk_bf16_f32 v12, v12, v13
	v_cvt_pk_bf16_f32 v13, v14, v15
	global_store_dwordx2 v[30:31], v[12:13], off offset:112
	ds_read_b128 v[12:15], v255 offset:256
	v_pk_mul_f32 v[32:33], v[90:91], v[2:3] op_sel_hi:[1,0]
	v_pk_mul_f32 v[34:35], v[88:89], v[2:3] op_sel_hi:[1,0]
	s_waitcnt lgkmcnt(0)
	v_pk_mul_f32 v[12:13], v[32:33], v[12:13]
	v_pk_mul_f32 v[14:15], v[34:35], v[14:15]
	v_cvt_pk_bf16_f32 v12, v12, v13
	v_cvt_pk_bf16_f32 v13, v14, v15
	global_store_dwordx2 v[30:31], v[12:13], off offset:128
	ds_read_b128 v[12:15], v255 offset:288
	v_pk_mul_f32 v[32:33], v[38:39], v[2:3] op_sel_hi:[1,0]
	v_pk_mul_f32 v[34:35], v[36:37], v[2:3] op_sel_hi:[1,0]
	s_waitcnt lgkmcnt(0)
	v_pk_mul_f32 v[12:13], v[32:33], v[12:13]
	v_pk_mul_f32 v[14:15], v[34:35], v[14:15]
	v_cvt_pk_bf16_f32 v12, v12, v13
	v_cvt_pk_bf16_f32 v13, v14, v15
	global_store_dwordx2 v[30:31], v[12:13], off offset:144
	ds_read_b128 v[12:15], v255 offset:320
	s_waitcnt lgkmcnt(0)
	v_pk_mul_f32 v[12:13], v[28:29], v[12:13]
	v_pk_mul_f32 v[14:15], v[26:27], v[14:15]
	v_cvt_pk_bf16_f32 v12, v12, v13
	v_cvt_pk_bf16_f32 v13, v14, v15
	global_store_dwordx2 v[30:31], v[12:13], off offset:160
	ds_read_b128 v[12:15], v255 offset:352
	s_waitcnt lgkmcnt(0)
	v_pk_mul_f32 v[12:13], v[24:25], v[12:13]
	v_pk_mul_f32 v[14:15], v[22:23], v[14:15]
	v_cvt_pk_bf16_f32 v12, v12, v13
	v_cvt_pk_bf16_f32 v13, v14, v15
	global_store_dwordx2 v[30:31], v[12:13], off offset:176
	ds_read_b128 v[12:15], v255 offset:384
	s_waitcnt lgkmcnt(0)
	v_pk_mul_f32 v[12:13], v[20:21], v[12:13]
	v_pk_mul_f32 v[14:15], v[18:19], v[14:15]
	v_cvt_pk_bf16_f32 v12, v12, v13
	v_cvt_pk_bf16_f32 v13, v14, v15
	global_store_dwordx2 v[30:31], v[12:13], off offset:192
	ds_read_b128 v[12:15], v255 offset:416
	s_waitcnt lgkmcnt(0)
	v_pk_mul_f32 v[8:9], v[8:9], v[12:13]
	v_pk_mul_f32 v[10:11], v[10:11], v[14:15]
	v_cvt_pk_bf16_f32 v8, v8, v9
	v_cvt_pk_bf16_f32 v9, v10, v11
	global_store_dwordx2 v[30:31], v[8:9], off offset:208
	ds_read_b128 v[8:11], v255 offset:448
	s_waitcnt lgkmcnt(0)
	v_pk_mul_f32 v[6:7], v[6:7], v[8:9]
	v_pk_mul_f32 v[4:5], v[4:5], v[10:11]
	v_cvt_pk_bf16_f32 v6, v6, v7
	v_cvt_pk_bf16_f32 v7, v4, v5
	global_store_dwordx2 v[30:31], v[6:7], off offset:224
	ds_read_b128 v[4:7], v255 offset:480
	v_pk_mul_f32 v[8:9], v[72:73], v[2:3] op_sel_hi:[1,0]
	v_pk_mul_f32 v[10:11], v[16:17], v[2:3] op_sel_hi:[1,0]
	s_waitcnt lgkmcnt(0)
	v_pk_mul_f32 v[4:5], v[8:9], v[4:5]
	v_pk_mul_f32 v[6:7], v[10:11], v[6:7]
	v_cvt_pk_bf16_f32 v4, v4, v5
	v_cvt_pk_bf16_f32 v5, v6, v7
	global_store_dwordx2 v[30:31], v[4:5], off offset:240
	s_branch .LBB0_154
.Lfa_entry:
	s_bitcmp0_b32 s58, 12
	s_cbranch_scc1 .Lfa_noprio
	s_setprio 1

; DI void attn_item(const Params& p, char* lds, int S, const bfr* Qb, const bfr* Kb, const bfr* Vtb, int h, int q0, int tok0) {
;     ...
;   for (int kt = 0; kt < nkt; ++kt) {
;     if (kt + 2 < nkt) WAIT_V(4); else if (kt + 1 < nkt) WAIT_V(2); else WAIT_V(0);
;     RAW_BARRIER();
;     if (kt + 3 < nkt) stage((kt + 3) & 3, kt + 3);
;     const char* sb = lds + 65536 + (kt & 3) * 16384;
;     const char* kimg = sb + c * 4096;
;     const char* vimg = sb + 8192;
;     f32x16 st[2];
;     {
;       bf16x8 kf[4];
; #pragma unroll
;       for (int ks = 0; ks < 4; ++ks) kf[ks] = *(const bf16x8*)(kimg + voffK[ks]);
; #pragma unroll
;       for (int t = 0; t < 2; ++t) {
;         const float negm = -m[t];
; #pragma unroll
;         for (int i = 0; i < 16; ++i) st[t][i] = negm;
; #pragma unroll
;         for (int ks = 0; ks < 4; ++ks) st[t] = MFMA(kf[ks], *(const bf16x8*)(qimg + t * 4096 + voffK[ks]), st[t]);
;       }
;     }
; #pragma unroll
;     for (int t = 0; t < 2; ++t) {
;       float mx = st[t][0];
; #pragma unroll
;       for (int i = 1; i < 16; ++i) mx = fmaxf(mx, st[t][i]);
;       mx = fmaxf(mx, __shfl_xor(mx, 32, 64));
;       if (__any(mx > 6.f)) {
;         const float d = fmaxf(mx, 0.f);
;         const float alpha = __builtin_amdgcn_exp2f(-d);
;         m[t] += d;
;         l[t] *= alpha;
; #pragma unroll
;         for (int i = 0; i < 16; ++i) st[t][i] -= d;
; #pragma unroll
;         for (int e = 0; e < 4; ++e)
; #pragma unroll
;           for (int i = 0; i < 16; ++i) O[t][e][i] *= alpha;
;       }
;     }
;     __builtin_amdgcn_iglp_opt(0);
; #pragma unroll
;     for (int t = 0; t < 2; ++t) {
;       float rs = 0.f;
; #pragma unroll
;       for (int i = 0; i < 16; ++i) { float pv = __builtin_amdgcn_exp2f(st[t][i]); st[t][i] = pv; rs += pv; }
;       l[t] += rs;
;       bf16x8 pf[2];
; #pragma unroll
;       for (int kc = 0; kc < 2; ++kc) {
;         u32x4 pp;
;         pp[0] = pk2(st[t][kc * 8 + 0], st[t][kc * 8 + 1]); pp[1] = pk2(st[t][kc * 8 + 2], st[t][kc * 8 + 3]);
;         pp[2] = pk2(st[t][kc * 8 + 4], st[t][kc * 8 + 5]); pp[3] = pk2(st[t][kc * 8 + 6], st[t][kc * 8 + 7]);
;         pf[kc] = __builtin_bit_cast(bf16x8, pp);
;       }
; #pragma unroll
;       for (int e = 0; e < 4; ++e)
; #pragma unroll
;         for (int kc = 0; kc < 2; ++kc) O[t][e] = MFMA(*(const bf16x8*)(vimg + e * 2048 + (voffV0 ^ (kc << 5))), pf[kc], O[t][e]);
;     }
.Lfa_loop:
	s_add_i32 s4, s0, 0xc000
	s_and_b32 s4, s4, 0xc000
	s_add_i32 s4, s58, s4
	s_waitcnt vmcnt(2)
	s_add_i32 s5, s4, 0x2000
	s_mov_b32 m0, s4
	s_barrier
	s_waitcnt lgkmcnt(2)
	v_mfma_f32_32x32x16_bf16 v[148:163], v[168:171], v[196:199], 0
	global_load_lds_dwordx4 v[164:165], off
	s_mov_b32 m0, s5
	s_and_b32 s4, s0, 0xc000
	global_load_lds_dwordx4 v[166:167], off
	ds_read_b128 v[196:199], v182 offset:4096
	s_bitset1_b32 s4, 16
	v_add_u32_e32 v255, s4, v209
	v_add_u32_e32 v254, s4, v210
	v_add_f32_e32 v180, v180, v132
	v_add_f32_e32 v180, v180, v133
	v_add_f32_e32 v180, v180, v134
	v_add_f32_e32 v180, v180, v135
	s_waitcnt lgkmcnt(2)
	v_mfma_f32_32x32x16_bf16 v[148:163], v[172:175], v[218:221], v[148:163]
	ds_read_b128 v[226:229], v255 offset:8192
	ds_read_b128 v[234:237], v255 offset:10240
	ds_read_b128 v[242:245], v255 offset:12288
	v_add_f32_e32 v180, v180, v136
	v_add_f32_e32 v180, v180, v137
	v_cvt_pk_bf16_f32 v132, v132, v133
	v_cvt_pk_bf16_f32 v133, v134, v135
	v_cvt_pk_bf16_f32 v134, v136, v137
	v_cvt_pk_bf16_f32 v135, v138, v139
	s_waitcnt lgkmcnt(4)
	v_mfma_f32_32x32x16_bf16 v[148:163], v[176:179], v[192:195], v[148:163]
	ds_read_b128 v[250:253], v255 offset:14336
	ds_read_b128 v[230:233], v254 offset:8192
	v_add_f32_e32 v180, v180, v138
	ds_read_b128 v[238:241], v254 offset:10240
	v_add_f32_e32 v180, v180, v139
	v_exp_f32_e32 v140, v140
	v_lshl_add_u64 v[164:165], v[164:165], 0, s[50:51]
	v_exp_f32_e32 v141, v141
	s_waitcnt lgkmcnt(6)
	v_mfma_f32_32x32x16_bf16 v[148:163], v[188:191], v[196:199], v[148:163]
	ds_read_b128 v[246:249], v254 offset:12288
	ds_read_b128 v[222:225], v254 offset:14336
	v_exp_f32_e32 v142, v142
	v_exp_f32_e32 v143, v143
	v_lshl_add_u64 v[166:167], v[166:167], 0, s[52:53]
	s_add_i32 s5, s0, 0x4000
	s_and_b32 s5, s5, 0xc000
	s_bitset1_b32 s5, 16
	s_or_b32 s5, s5, s3
	s_waitcnt lgkmcnt(7)
	v_exp_f32_e32 v144, v144
	v_mfma_f32_32x32x16_bf16 v[116:131], v[226:229], v[132:135], v[116:131]
	v_exp_f32_e32 v145, v145
	v_add_f32_e32 v180, v180, v140
	v_add_u32_e32 v200, s5, v203
	ds_read_b128 v[168:171], v200
	s_waitcnt lgkmcnt(7)
	v_mfma_f32_32x32x16_bf16 v[100:115], v[234:237], v[132:135], v[100:115]
	v_exp_f32_e32 v146, v146
	v_exp_f32_e32 v147, v147
	v_add_f32_e32 v180, v180, v141
	v_add_u32_e32 v200, s5, v204
	ds_read_b128 v[172:175], v200
	s_waitcnt lgkmcnt(7)
	v_add_f32_e32 v180, v180, v142
	v_mfma_f32_32x32x16_bf16 v[84:99], v[242:245], v[132:135], v[84:99]
	v_add_f32_e32 v180, v180, v143
	v_add_f32_e32 v180, v180, v144
	v_add_f32_e32 v180, v180, v145
	v_add_u32_e32 v200, s5, v205
	ds_read_b128 v[176:179], v200
	s_waitcnt lgkmcnt(7)
	v_mfma_f32_32x32x16_bf16 v[68:83], v[250:253], v[132:135], v[68:83]
	v_cvt_pk_bf16_f32 v140, v140, v141
	v_cvt_pk_bf16_f32 v141, v142, v143
	v_cvt_pk_bf16_f32 v142, v144, v145
	v_add_f32_e32 v180, v180, v146
	v_cvt_pk_bf16_f32 v143, v146, v147
	v_add_f32_e32 v180, v180, v147
	v_add_u32_e32 v200, s5, v206
	ds_read_b128 v[188:191], v200
	s_waitcnt lgkmcnt(7)
	v_exp_f32_e32 v148, v148
	v_mfma_f32_32x32x16_bf16 v[116:131], v[230:233], v[140:143], v[116:131]
	v_exp_f32_e32 v149, v149
	v_exp_f32_e32 v150, v150
	s_waitcnt lgkmcnt(6)
	v_exp_f32_e32 v151, v151
	v_mfma_f32_32x32x16_bf16 v[100:115], v[238:241], v[140:143], v[100:115]
	v_add_f32_e32 v181, v181, v148
	v_exp_f32_e32 v152, v152
	v_add_f32_e32 v181, v181, v149
	v_exp_f32_e32 v153, v153
	s_waitcnt lgkmcnt(5)
	v_add_f32_e32 v181, v181, v150
	v_mfma_f32_32x32x16_bf16 v[84:99], v[246:249], v[140:143], v[84:99]
	v_exp_f32_e32 v154, v154
	v_add_f32_e32 v181, v181, v151
	v_exp_f32_e32 v155, v155
	v_add_f32_e32 v181, v181, v152
	v_add_f32_e32 v181, v181, v153
	s_waitcnt lgkmcnt(4)
	v_mfma_f32_32x32x16_bf16 v[68:83], v[222:225], v[140:143], v[68:83]
	v_cvt_pk_bf16_f32 v148, v148, v149
	v_cvt_pk_bf16_f32 v149, v150, v151
	v_cvt_pk_bf16_f32 v150, v152, v153
	v_cvt_pk_bf16_f32 v151, v154, v155
	v_add_f32_e32 v181, v181, v154
	v_add_f32_e32 v181, v181, v155
	v_mfma_f32_32x32x16_bf16 v[52:67], v[226:229], v[148:151], v[52:67]
	v_exp_f32_e32 v156, v156
	v_exp_f32_e32 v157, v157
	ds_read_b128 v[192:195], v185
	v_mfma_f32_32x32x16_bf16 v[36:51], v[234:237], v[148:151], v[36:51]
	v_exp_f32_e32 v158, v158
	v_exp_f32_e32 v159, v159
	ds_read_b128 v[196:199], v184
	v_mfma_f32_32x32x16_bf16 v[20:35], v[242:245], v[148:151], v[20:35]
	v_exp_f32_e32 v160, v160
	v_exp_f32_e32 v161, v161
	ds_read_b128 v[218:221], v183
	v_mfma_f32_32x32x16_bf16 v[4:19], v[250:253], v[148:151], v[4:19]
	v_add_f32_e32 v181, v181, v156
	v_exp_f32_e32 v162, v162
	v_exp_f32_e32 v163, v163
	v_add_f32_e32 v181, v181, v157
	s_waitcnt lgkmcnt(2)
	v_mfma_f32_32x32x16_bf16 v[132:147], v[168:171], v[192:195], 0
	v_add_f32_e32 v181, v181, v158
	ds_read_b128 v[192:195], v182
	v_add_f32_e32 v181, v181, v159
	v_add_f32_e32 v181, v181, v160
	v_add_f32_e32 v181, v181, v161
	s_waitcnt lgkmcnt(2)
	v_mfma_f32_32x32x16_bf16 v[132:147], v[172:175], v[196:199], v[132:147]
	v_cvt_pk_bf16_f32 v156, v156, v157
	v_cvt_pk_bf16_f32 v157, v158, v159
	v_cvt_pk_bf16_f32 v158, v160, v161
	v_cvt_pk_bf16_f32 v159, v162, v163
	v_add_f32_e32 v181, v181, v162
	v_add_f32_e32 v181, v181, v163
	ds_read_b128 v[196:199], v185 offset:4096
	s_waitcnt lgkmcnt(2)
	v_mfma_f32_32x32x16_bf16 v[132:147], v[176:179], v[218:221], v[132:147]
	s_add_i32 s1, s1, 1
	ds_read_b128 v[218:221], v184 offset:4096
	s_addk_i32 s0, 0x4000
	s_waitcnt lgkmcnt(2)
	v_mfma_f32_32x32x16_bf16 v[132:147], v[188:191], v[192:195], v[132:147]
	ds_read_b128 v[192:195], v183 offset:4096
	v_mfma_f32_32x32x16_bf16 v[52:67], v[230:233], v[156:159], v[52:67]
	s_nop 3
	v_mfma_f32_32x32x16_bf16 v[36:51], v[238:241], v[156:159], v[36:51]
	s_nop 3
	v_mfma_f32_32x32x16_bf16 v[20:35], v[246:249], v[156:159], v[20:35]
	v_exp_f32_e32 v132, v132
	v_exp_f32_e32 v133, v133
	v_exp_f32_e32 v134, v134
	v_exp_f32_e32 v135, v135
	v_mfma_f32_32x32x16_bf16 v[4:19], v[222:225], v[156:159], v[4:19]
	v_exp_f32_e32 v136, v136
	v_exp_f32_e32 v137, v137
	v_exp_f32_e32 v138, v138
	v_exp_f32_e32 v139, v139
	s_cmp_eq_u32 s38, s1
	s_cbranch_scc0 .Lfa_loop
	v_mov_b32_e32 v186, 0
	v_mov_b32_e32 v187, 0
	v_cmp_lt_i32_e32 vcc, v213, v214
	s_nop 1
	v_cndmask_b32_e32 v2, v212, v213, vcc
	v_lshlrev_b32_e32 v216, 2, v2
	s_setprio 0
	s_branch .LBB0_165
